# K1 + half mode also skips the unused B1 LDS reads and SB(.,1) DMA loads, counted waits vmcnt(6)
# speedup vs baseline: 1.0594x; 1.0019x over previous
.LBB0_477:
	s_add_u32 s6, s0, 0xfffc0080
	s_addc_u32 s7, s1, -1
	s_add_i32 s85, 0, 0x10000
	s_cmp_eq_u32 s84, 12
	s_cselect_b32 s31, s17, s7
	s_cselect_b32 s30, s80, s6
	s_cselect_b32 s7, s15, s83
	s_cselect_b32 s6, s81, s82
	s_add_i32 s88, 0, 0x14000
	v_add_u32_e32 v154, s85, v144
	v_add_u32_e32 v170, s88, v144
	.p2align 6
	ds_read_b128 v[140:143], v154
	ds_read_b128 v[146:149], v154 offset:1024
	ds_read_b128 v[150:153], v154 offset:2048
	ds_read_b128 v[154:157], v154 offset:3072
	s_cmp_eq_u32 s101, 1
	s_cbranch_scc1 .Lk0_rb1
	ds_read_b128 v[158:161], v170
	ds_read_b128 v[162:165], v170 offset:1024
	ds_read_b128 v[166:169], v170 offset:2048
	ds_read_b128 v[170:173], v170 offset:3072
.Lk0_rb1:
	v_lshl_add_u64 v[182:183], s[0:1], 0, v[138:139]
	s_add_i32 m0, s60, 0xc000
	ds_read_b128 v[174:177], v145
	ds_read_b128 v[178:181], v145 offset:1024
	ds_read_b128 v[200:203], v145 offset:2048
	ds_read_b128 v[204:207], v145 offset:3072
	ds_read_b128 v[208:211], v145 offset:4096
	ds_read_b128 v[212:215], v145 offset:5120
	ds_read_b128 v[222:225], v145 offset:6144
	ds_read_b128 v[226:229], v145 offset:7168
	global_load_lds_dwordx4 v[182:183], off
	v_lshl_add_u64 v[182:183], s[0:1], 0, v[136:137]
	s_add_i32 m0, s60, 0xe000
	s_nop 0
	global_load_lds_dwordx4 v[182:183], off
	s_waitcnt vmcnt(8)
	s_cmp_lg_u32 s101, 1
	s_cbranch_scc1 .Lk0_w1
	s_waitcnt vmcnt(6)
.Lk0_w1:
	s_waitcnt lgkmcnt(0)
	s_barrier
	s_setprio 1
	s_waitcnt lgkmcnt(0)
	v_mfma_f32_16x16x32_bf16 v[126:129], v[140:143], v[174:177], v[126:129]
	v_mfma_f32_16x16x32_bf16 v[122:125], v[150:153], v[174:177], v[122:125]
	v_mfma_f32_16x16x32_bf16 v[114:117], v[140:143], v[200:203], v[114:117]
	v_mfma_f32_16x16x32_bf16 v[106:109], v[150:153], v[200:203], v[106:109]
	v_mfma_f32_16x16x32_bf16 v[98:101], v[140:143], v[208:211], v[98:101]
	v_mfma_f32_16x16x32_bf16 v[90:93], v[150:153], v[208:211], v[90:93]
	v_mfma_f32_16x16x32_bf16 v[82:85], v[140:143], v[222:225], v[82:85]
	v_mfma_f32_16x16x32_bf16 v[72:75], v[150:153], v[222:225], v[72:75]
	v_mfma_f32_16x16x32_bf16 v[126:129], v[146:149], v[178:181], v[126:129]
	v_mfma_f32_16x16x32_bf16 v[122:125], v[154:157], v[178:181], v[122:125]
	v_mfma_f32_16x16x32_bf16 v[114:117], v[146:149], v[204:207], v[114:117]
	v_mfma_f32_16x16x32_bf16 v[106:109], v[154:157], v[204:207], v[106:109]
	v_mfma_f32_16x16x32_bf16 v[98:101], v[146:149], v[212:215], v[98:101]
	v_mfma_f32_16x16x32_bf16 v[90:93], v[154:157], v[212:215], v[90:93]
	v_mfma_f32_16x16x32_bf16 v[82:85], v[146:149], v[226:229], v[82:85]
	v_mfma_f32_16x16x32_bf16 v[72:75], v[154:157], v[226:229], v[72:75]
	s_setprio 0
	s_cmp_eq_u32 s101, 1
	s_cbranch_scc1 .Lk0_half1
	s_setprio 1
	v_mfma_f32_16x16x32_bf16 v[118:121], v[158:161], v[174:177], v[118:121]
	v_mfma_f32_16x16x32_bf16 v[110:113], v[166:169], v[174:177], v[110:113]
	v_mfma_f32_16x16x32_bf16 v[102:105], v[158:161], v[200:203], v[102:105]
	v_mfma_f32_16x16x32_bf16 v[94:97], v[166:169], v[200:203], v[94:97]
	v_mfma_f32_16x16x32_bf16 v[86:89], v[158:161], v[208:211], v[86:89]
	v_mfma_f32_16x16x32_bf16 v[76:79], v[166:169], v[208:211], v[76:79]
	v_mfma_f32_16x16x32_bf16 v[68:71], v[158:161], v[222:225], v[68:71]
	v_mfma_f32_16x16x32_bf16 v[64:67], v[166:169], v[222:225], v[64:67]
	v_mfma_f32_16x16x32_bf16 v[118:121], v[162:165], v[178:181], v[118:121]
	v_mfma_f32_16x16x32_bf16 v[110:113], v[170:173], v[178:181], v[110:113]
	v_mfma_f32_16x16x32_bf16 v[102:105], v[162:165], v[204:207], v[102:105]
	v_mfma_f32_16x16x32_bf16 v[94:97], v[170:173], v[204:207], v[94:97]
	v_mfma_f32_16x16x32_bf16 v[86:89], v[162:165], v[212:215], v[86:89]
	v_mfma_f32_16x16x32_bf16 v[76:79], v[170:173], v[212:215], v[76:79]
	v_mfma_f32_16x16x32_bf16 v[68:71], v[162:165], v[226:229], v[68:71]
	v_mfma_f32_16x16x32_bf16 v[64:67], v[170:173], v[226:229], v[64:67]
	s_setprio 0
.Lk0_half1:
	s_barrier
	s_add_i32 s85, s85, s39
	v_lshl_add_u64 v[182:183], s[6:7], 0, v[80:81]
	s_mov_b32 m0, s85
	ds_read_b128 v[174:177], v145 offset:16384
	ds_read_b128 v[178:181], v145 offset:17408
	ds_read_b128 v[200:203], v145 offset:18432
	ds_read_b128 v[204:207], v145 offset:19456
	ds_read_b128 v[208:211], v145 offset:20480
	ds_read_b128 v[212:215], v145 offset:21504
	ds_read_b128 v[222:225], v145 offset:22528
	ds_read_b128 v[226:229], v145 offset:23552
	global_load_lds_dwordx4 v[182:183], off
	s_add_i32 m0, s85, 0x2000
	s_add_u32 s86, s6, 0x40000
	v_lshl_add_u64 v[184:185], s[6:7], 0, v[130:131]
	s_addc_u32 s87, s7, 0
	s_add_i32 s85, s88, s39
	global_load_lds_dwordx4 v[184:185], off
	v_lshl_add_u64 v[188:189], s[86:87], 0, v[80:81]
	s_mov_b32 m0, s85
	v_lshl_add_u64 v[190:191], s[30:31], 0, v[132:133]
	s_cmp_eq_u32 s101, 1
	s_cbranch_scc1 .Lk0_nb1a
	global_load_lds_dwordx4 v[188:189], off
	v_lshl_add_u64 v[188:189], s[86:87], 0, v[130:131]
	s_add_i32 m0, s85, 0x2000
	s_nop 0
	global_load_lds_dwordx4 v[188:189], off
.Lk0_nb1a:
	v_lshl_add_u64 v[188:189], s[30:31], 0, v[134:135]
	s_mov_b32 m0, s60
	s_nop 0
	global_load_lds_dwordx4 v[188:189], off
	s_mov_b32 m0, s61
	s_nop 0
	global_load_lds_dwordx4 v[190:191], off
	s_waitcnt vmcnt(8)
	s_cmp_lg_u32 s101, 1
	s_cbranch_scc1 .Lk0_w2
	s_waitcnt vmcnt(6)
.Lk0_w2:
	s_waitcnt lgkmcnt(0)
	s_barrier
	s_setprio 1
	s_waitcnt lgkmcnt(0)
	v_mfma_f32_16x16x32_bf16 v[60:63], v[140:143], v[174:177], v[60:63]
	v_mfma_f32_16x16x32_bf16 v[56:59], v[150:153], v[174:177], v[56:59]
	v_mfma_f32_16x16x32_bf16 v[48:51], v[140:143], v[200:203], v[48:51]
	v_mfma_f32_16x16x32_bf16 v[40:43], v[150:153], v[200:203], v[40:43]
	v_mfma_f32_16x16x32_bf16 v[32:35], v[140:143], v[208:211], v[32:35]
	v_mfma_f32_16x16x32_bf16 v[24:27], v[150:153], v[208:211], v[24:27]
	v_mfma_f32_16x16x32_bf16 v[16:19], v[140:143], v[222:225], v[16:19]
	v_mfma_f32_16x16x32_bf16 v[8:11], v[150:153], v[222:225], v[8:11]
	v_mfma_f32_16x16x32_bf16 v[60:63], v[146:149], v[178:181], v[60:63]
	v_mfma_f32_16x16x32_bf16 v[56:59], v[154:157], v[178:181], v[56:59]
	v_mfma_f32_16x16x32_bf16 v[48:51], v[146:149], v[204:207], v[48:51]
	v_mfma_f32_16x16x32_bf16 v[40:43], v[154:157], v[204:207], v[40:43]
	v_mfma_f32_16x16x32_bf16 v[32:35], v[146:149], v[212:215], v[32:35]
	v_mfma_f32_16x16x32_bf16 v[24:27], v[154:157], v[212:215], v[24:27]
	v_mfma_f32_16x16x32_bf16 v[16:19], v[146:149], v[226:229], v[16:19]
	v_mfma_f32_16x16x32_bf16 v[8:11], v[154:157], v[226:229], v[8:11]
	s_setprio 0
	s_cmp_eq_u32 s101, 1
	s_cbranch_scc1 .Lk0_half2
	s_setprio 1
	v_mfma_f32_16x16x32_bf16 v[52:55], v[158:161], v[174:177], v[52:55]
	v_mfma_f32_16x16x32_bf16 v[44:47], v[166:169], v[174:177], v[44:47]
	v_mfma_f32_16x16x32_bf16 v[36:39], v[158:161], v[200:203], v[36:39]
	v_mfma_f32_16x16x32_bf16 v[28:31], v[166:169], v[200:203], v[28:31]
	v_mfma_f32_16x16x32_bf16 v[20:23], v[158:161], v[208:211], v[20:23]
	v_mfma_f32_16x16x32_bf16 v[12:15], v[166:169], v[208:211], v[12:15]
	v_mfma_f32_16x16x32_bf16 v[4:7], v[158:161], v[222:225], v[4:7]
	v_mfma_f32_16x16x32_bf16 v[0:3], v[166:169], v[222:225], v[0:3]
	v_mfma_f32_16x16x32_bf16 v[52:55], v[162:165], v[178:181], v[52:55]
	v_mfma_f32_16x16x32_bf16 v[44:47], v[170:173], v[178:181], v[44:47]
	v_mfma_f32_16x16x32_bf16 v[36:39], v[162:165], v[204:207], v[36:39]
	v_mfma_f32_16x16x32_bf16 v[28:31], v[170:173], v[204:207], v[28:31]
	v_mfma_f32_16x16x32_bf16 v[20:23], v[162:165], v[212:215], v[20:23]
	v_mfma_f32_16x16x32_bf16 v[12:15], v[170:173], v[212:215], v[12:15]
	v_mfma_f32_16x16x32_bf16 v[4:7], v[162:165], v[226:229], v[4:7]
	v_mfma_f32_16x16x32_bf16 v[0:3], v[170:173], v[226:229], v[0:3]
	s_setprio 0
.Lk0_half2:
	s_barrier
	s_add_i32 s85, 0, 0x18000
	s_add_i32 s86, 0, 0x1c000
	v_add_u32_e32 v154, s85, v144
	v_add_u32_e32 v170, s86, v144
	ds_read_b128 v[140:143], v154
	ds_read_b128 v[146:149], v154 offset:1024
	ds_read_b128 v[150:153], v154 offset:2048
	ds_read_b128 v[154:157], v154 offset:3072
	s_cmp_eq_u32 s101, 1
	s_cbranch_scc1 .Lk0_rb2
	ds_read_b128 v[158:161], v170
	ds_read_b128 v[162:165], v170 offset:1024
	ds_read_b128 v[166:169], v170 offset:2048
	ds_read_b128 v[170:173], v170 offset:3072
.Lk0_rb2:
	s_add_u32 s30, s30, 0x40000
	s_addc_u32 s31, s31, 0
	s_mov_b32 m0, s62
	v_lshl_add_u64 v[192:193], s[30:31], 0, v[134:135]
	ds_read_b128 v[174:177], v145 offset:32768
	ds_read_b128 v[178:181], v145 offset:33792
	ds_read_b128 v[200:203], v145 offset:34816
	ds_read_b128 v[204:207], v145 offset:35840
	ds_read_b128 v[208:211], v145 offset:36864
	ds_read_b128 v[212:215], v145 offset:37888
	ds_read_b128 v[222:225], v145 offset:38912
	ds_read_b128 v[226:229], v145 offset:39936
	global_load_lds_dwordx4 v[192:193], off
	v_lshl_add_u64 v[192:193], s[30:31], 0, v[132:133]
	s_mov_b32 m0, s63
	s_nop 0
	global_load_lds_dwordx4 v[192:193], off
	s_waitcnt vmcnt(8)
	s_cmp_lg_u32 s101, 1
	s_cbranch_scc1 .Lk0_w3
	s_waitcnt vmcnt(6)

.Lk0_half3:
	s_barrier
	s_add_i32 s30, s85, s39
	v_lshl_add_u64 v[182:183], v[182:183], 0, s[12:13]
	s_mov_b32 m0, s30
	ds_read_b128 v[174:177], v145 offset:49152
	ds_read_b128 v[178:181], v145 offset:50176
	ds_read_b128 v[200:203], v145 offset:51200
	ds_read_b128 v[204:207], v145 offset:52224
	ds_read_b128 v[208:211], v145 offset:53248
	ds_read_b128 v[212:215], v145 offset:54272
	ds_read_b128 v[222:225], v145 offset:55296
	ds_read_b128 v[226:229], v145 offset:56320
	global_load_lds_dwordx4 v[182:183], off
	s_add_i32 m0, s30, 0x2000
	s_add_u32 s6, s6, 0x40080
	v_lshl_add_u64 v[182:183], v[184:185], 0, s[12:13]
	s_addc_u32 s7, s7, 0
	s_add_i32 s30, s86, s39
	global_load_lds_dwordx4 v[182:183], off
	s_cmp_eq_u32 s101, 1
	s_cbranch_scc1 .Lk0_nb1b
	v_lshl_add_u64 v[182:183], s[6:7], 0, v[80:81]
	s_mov_b32 m0, s30
	s_nop 0
	global_load_lds_dwordx4 v[182:183], off
	v_lshl_add_u64 v[182:183], s[6:7], 0, v[130:131]
	s_add_i32 m0, s30, 0x2000
	s_nop 0
	global_load_lds_dwordx4 v[182:183], off
.Lk0_nb1b:
	v_lshl_add_u64 v[182:183], v[188:189], 0, s[12:13]
	s_mov_b32 m0, s66
	s_nop 0
	global_load_lds_dwordx4 v[182:183], off
	v_lshl_add_u64 v[182:183], v[190:191], 0, s[12:13]
	s_mov_b32 m0, s67
	s_nop 0
	global_load_lds_dwordx4 v[182:183], off
	s_waitcnt vmcnt(8)
	s_cmp_lg_u32 s101, 1
	s_cbranch_scc1 .Lk0_w4
	s_waitcnt vmcnt(6)
